# flash softmax cross-quad reductions via v_permlane16/32_swap instead of ds_bpermute (diff + swa)
# speedup vs baseline: 1.0109x; 1.0052x over previous
.LBB0_986:
	v_max3_f32 v2, v96, s76, v97
	v_max3_f32 v2, v2, v98, v99
	v_max3_f32 v2, v2, v92, v93
	v_max3_f32 v2, v2, v94, v95
	v_max3_f32 v2, v2, v88, v89
	v_max3_f32 v2, v2, v90, v91
	v_max3_f32 v2, v2, v84, v85
	v_max3_f32 v2, v2, v86, v87
	v_mov_b32_e32 v3, v2
	s_nop 1
	v_permlane16_swap_b32 v3, v2
	s_waitcnt lgkmcnt(0)
	v_max_f32_e32 v3, v3, v3
	v_max_f32_e32 v2, v2, v3
	v_mov_b32_e32 v3, v2
	s_nop 1
	v_permlane32_swap_b32 v3, v2
	s_waitcnt lgkmcnt(0)
	v_max3_f32 v2, v124, v2, v3
	v_mul_f32_e32 v3, 0xbfb8aa3b, v2
	v_fmamk_f32 v96, v96, 0x3fb8aa3b, v3
	v_fmamk_f32 v97, v97, 0x3fb8aa3b, v3
	v_fmamk_f32 v125, v93, 0x3fb8aa3b, v3
	v_exp_f32_e32 v93, v96
	v_fmamk_f32 v98, v98, 0x3fb8aa3b, v3
	v_fmamk_f32 v126, v94, 0x3fb8aa3b, v3
	v_exp_f32_e32 v94, v97
	v_fmamk_f32 v99, v99, 0x3fb8aa3b, v3
	v_exp_f32_e32 v96, v98
	v_fmamk_f32 v92, v92, 0x3fb8aa3b, v3
	v_exp_f32_e32 v97, v99
	v_exp_f32_e32 v98, v92
	v_add_f32_e32 v92, 0, v93
	v_exp_f32_e32 v99, v125
	v_add_f32_e32 v92, v94, v92
	v_add_f32_e32 v92, v96, v92
	v_exp_f32_e32 v125, v126
	v_fmamk_f32 v95, v95, 0x3fb8aa3b, v3
	v_add_f32_e32 v92, v97, v92
	v_exp_f32_e32 v95, v95
	v_fmamk_f32 v88, v88, 0x3fb8aa3b, v3
	v_add_f32_e32 v92, v98, v92
	v_exp_f32_e32 v88, v88
	v_fmamk_f32 v89, v89, 0x3fb8aa3b, v3
	v_add_f32_e32 v92, v99, v92
	v_exp_f32_e32 v89, v89
	v_fmamk_f32 v90, v90, 0x3fb8aa3b, v3
	v_add_f32_e32 v92, v125, v92
	v_exp_f32_e32 v90, v90
	v_fmamk_f32 v91, v91, 0x3fb8aa3b, v3
	v_add_f32_e32 v92, v95, v92
	v_exp_f32_e32 v91, v91
	v_add_f32_e32 v92, v88, v92
	v_add_f32_e32 v92, v89, v92
	v_add_f32_e32 v92, v90, v92
	v_fmamk_f32 v84, v84, 0x3fb8aa3b, v3
	v_add_f32_e32 v126, v91, v92
	v_exp_f32_e32 v92, v84
	v_fmamk_f32 v84, v85, 0x3fb8aa3b, v3
	v_exp_f32_e32 v85, v84
	v_fmamk_f32 v84, v86, 0x3fb8aa3b, v3
	v_exp_f32_e32 v86, v84
	v_fmac_f32_e32 v3, 0x3fb8aa3b, v87
	v_exp_f32_e32 v87, v3
	v_add_f32_e32 v3, v92, v126
	v_add_f32_e32 v3, v85, v3
	v_add_f32_e32 v3, v86, v3
	v_add_f32_e32 v3, v87, v3
	v_mov_b32_e32 v84, v3
	s_nop 1
	v_permlane16_swap_b32 v84, v3
	v_sub_f32_e32 v124, v124, v2
	v_mul_f32_e32 v124, 0x3fb8aa3b, v124
	v_exp_f32_e32 v124, v124
	s_waitcnt lgkmcnt(0)
	v_add_f32_e32 v126, v3, v84
	v_mov_b32_e32 v127, v126
	s_nop 1
	v_permlane32_swap_b32 v127, v126
	v_cmp_neq_f32_e32 vcc, 1.0, v124
	s_cbranch_vccz .LBB0_988
	ds_bpermute_b32 v128, v111, v124
	ds_bpermute_b32 v130, v117, v124
	ds_bpermute_b32 v131, v118, v124
	ds_bpermute_b32 v129, v116, v124
	s_waitcnt lgkmcnt(1)
	v_pk_mul_f32 v[62:63], v[62:63], v[130:131]
	s_waitcnt lgkmcnt(0)
	v_pk_mul_f32 v[60:61], v[60:61], v[128:129]
	v_pk_mul_f32 v[50:51], v[50:51], v[130:131]
	v_pk_mul_f32 v[48:49], v[48:49], v[128:129]
	v_pk_mul_f32 v[54:55], v[54:55], v[130:131]
	v_pk_mul_f32 v[52:53], v[52:53], v[128:129]
	v_pk_mul_f32 v[66:67], v[66:67], v[130:131]
	v_pk_mul_f32 v[64:65], v[64:65], v[128:129]
.LBB0_988:
	v_max3_f32 v3, v80, s76, v81
	v_max3_f32 v3, v3, v82, v83
	v_max3_f32 v3, v3, v76, v77
	v_max3_f32 v3, v3, v78, v79
	v_max3_f32 v3, v3, v72, v73
	v_max3_f32 v3, v3, v74, v75
	v_max3_f32 v3, v3, v68, v69
	v_max3_f32 v3, v3, v70, v71
	v_mov_b32_e32 v84, v3
	s_nop 1
	v_permlane16_swap_b32 v84, v3
	s_waitcnt lgkmcnt(0)
	v_max_f32_e32 v84, v84, v84
	v_max_f32_e32 v3, v3, v84
	v_mov_b32_e32 v84, v3
	s_nop 1
	v_permlane32_swap_b32 v84, v3
	s_waitcnt lgkmcnt(0)
	v_max3_f32 v84, v110, v3, v84
	v_mul_f32_e32 v3, 0xbfb8aa3b, v84
	v_fmamk_f32 v80, v80, 0x3fb8aa3b, v3
	v_fmamk_f32 v81, v81, 0x3fb8aa3b, v3
	v_fmamk_f32 v128, v77, 0x3fb8aa3b, v3
	v_exp_f32_e32 v77, v80
	v_fmamk_f32 v82, v82, 0x3fb8aa3b, v3
	v_fmamk_f32 v129, v78, 0x3fb8aa3b, v3
	v_exp_f32_e32 v78, v81
	v_fmamk_f32 v83, v83, 0x3fb8aa3b, v3
	v_exp_f32_e32 v80, v82
	v_fmamk_f32 v76, v76, 0x3fb8aa3b, v3
	v_exp_f32_e32 v81, v83
	v_exp_f32_e32 v82, v76
	v_add_f32_e32 v76, 0, v77
	v_exp_f32_e32 v83, v128
	v_add_f32_e32 v76, v78, v76
	v_add_f32_e32 v76, v80, v76
	v_exp_f32_e32 v128, v129
	v_fmamk_f32 v79, v79, 0x3fb8aa3b, v3
	v_add_f32_e32 v76, v81, v76
	v_exp_f32_e32 v79, v79
	v_fmamk_f32 v72, v72, 0x3fb8aa3b, v3
	v_add_f32_e32 v76, v82, v76
	v_exp_f32_e32 v72, v72
	v_fmamk_f32 v73, v73, 0x3fb8aa3b, v3
	v_add_f32_e32 v76, v83, v76
	v_exp_f32_e32 v73, v73
	v_fmamk_f32 v74, v74, 0x3fb8aa3b, v3
	v_add_f32_e32 v76, v128, v76
	v_exp_f32_e32 v74, v74
	v_fmamk_f32 v75, v75, 0x3fb8aa3b, v3
	v_add_f32_e32 v76, v79, v76
	v_exp_f32_e32 v75, v75
	v_add_f32_e32 v76, v72, v76
	v_add_f32_e32 v76, v73, v76
	v_add_f32_e32 v76, v74, v76
	v_fmamk_f32 v68, v68, 0x3fb8aa3b, v3
	v_add_f32_e32 v129, v75, v76
	v_exp_f32_e32 v76, v68
	v_fmamk_f32 v68, v69, 0x3fb8aa3b, v3
	v_exp_f32_e32 v69, v68
	v_fmamk_f32 v68, v70, 0x3fb8aa3b, v3
	v_exp_f32_e32 v70, v68
	v_fmac_f32_e32 v3, 0x3fb8aa3b, v71
	v_exp_f32_e32 v71, v3
	v_add_f32_e32 v3, v76, v129
	v_add_f32_e32 v3, v69, v3
	v_add_f32_e32 v3, v70, v3
	v_add_f32_e32 v3, v71, v3
	v_mov_b32_e32 v129, v3
	s_nop 1
	v_permlane16_swap_b32 v129, v3
	v_sub_f32_e32 v68, v110, v84
	v_mul_f32_e32 v68, 0x3fb8aa3b, v68
	v_exp_f32_e32 v68, v68
	s_waitcnt lgkmcnt(0)
	v_add_f32_e32 v3, v3, v129
	v_mov_b32_e32 v110, v3
	s_nop 1
	v_permlane32_swap_b32 v110, v3
	v_cmp_neq_f32_e32 vcc, 1.0, v68
	s_cbranch_vccz .LBB0_990
	ds_bpermute_b32 v130, v111, v68
	ds_bpermute_b32 v132, v117, v68
	ds_bpermute_b32 v133, v118, v68
	ds_bpermute_b32 v131, v116, v68
	s_waitcnt lgkmcnt(1)
	v_pk_mul_f32 v[38:39], v[38:39], v[132:133]
	s_waitcnt lgkmcnt(0)
	v_pk_mul_f32 v[36:37], v[36:37], v[130:131]
	v_pk_mul_f32 v[42:43], v[42:43], v[132:133]
	v_pk_mul_f32 v[40:41], v[40:41], v[130:131]
	v_pk_mul_f32 v[46:47], v[46:47], v[132:133]
	v_pk_mul_f32 v[44:45], v[44:45], v[130:131]
	v_pk_mul_f32 v[58:59], v[58:59], v[132:133]
	v_pk_mul_f32 v[56:57], v[56:57], v[130:131]

.LBB0_1310:
	s_mov_b32 s10, s2
	s_add_i32 s10, s45, s10
	s_add_i32 s2, s2, 1
	s_add_i32 s10, s10, 33
	s_cmp_lt_u32 s2, s36
	s_cselect_b32 s11, s2, s10
	s_lshl_b32 s10, s11, 6
	s_cmp_lt_i32 s11, 32
	s_cselect_b32 s11, s8, s9
	s_add_i32 s11, s11, s10
	v_add_u32_e32 v2, s11, v150
	v_mad_i64_i32 v[2:3], s[20:21], v2, s6, v[130:131]
	s_barrier
	s_waitcnt vmcnt(5)
	ds_write_b128 v154, v[84:87]
	s_waitcnt vmcnt(4)
	ds_write_b128 v155, v[88:91]
	s_waitcnt vmcnt(3)
	ds_write_b128 v154, v[92:95] offset:9216
	s_waitcnt vmcnt(2)
	ds_write_b128 v155, v[96:99] offset:9216
	s_waitcnt vmcnt(1)
	ds_write_b128 v156, v[100:103] offset:9216
	s_waitcnt vmcnt(0)
	ds_write_b128 v157, v[104:107] offset:9216
	s_waitcnt lgkmcnt(0)
	s_barrier
	global_load_dwordx4 v[84:87], v[2:3], off
	v_add_u32_e32 v2, s11, v151
	s_ashr_i32 s11, s10, 31
	v_mad_i64_i32 v[2:3], s[20:21], v2, s6, v[130:131]
	s_lshl_b64 s[10:11], s[10:11], 1
	global_load_dwordx4 v[88:91], v[2:3], off
	v_lshl_add_u64 v[2:3], v[132:133], 0, s[10:11]
	global_load_dwordx4 v[92:95], v[2:3], off
	v_lshl_add_u64 v[2:3], v[134:135], 0, s[10:11]
	global_load_dwordx4 v[96:99], v[2:3], off
	v_lshl_add_u64 v[2:3], v[136:137], 0, s[10:11]
	global_load_dwordx4 v[100:103], v[2:3], off
	v_lshl_add_u64 v[2:3], v[138:139], 0, s[10:11]
	global_load_dwordx4 v[104:107], v[2:3], off
	v_add_u32_e32 v2, v152, v153
	ds_read_b128 v[108:111], v2
	ds_read_b128 v[116:119], v2 offset:64
	s_waitcnt lgkmcnt(1)
	v_mfma_f32_16x16x32_bf16 v[112:115], v[108:111], v[72:75], 0
	ds_read_b128 v[120:123], v2 offset:2368
	ds_read_b128 v[166:169], v2 offset:4672
	v_mov_b32_e32 v174, v159
	s_waitcnt lgkmcnt(2)
	v_mfma_f32_16x16x32_bf16 v[124:127], v[116:119], v[68:71], v[112:115]
	ds_read_b128 v[170:173], v2 offset:6976
	s_nop 1
	ds_read_b128 v[112:115], v2 offset:2304
	v_mfma_f32_16x16x32_bf16 v[108:111], v[108:111], v[76:79], 0
	s_nop 2
	v_max3_f32 v3, v124, s76, v125
	v_max3_f32 v3, v3, v126, v127
	v_mfma_f32_16x16x32_bf16 v[108:111], v[116:119], v[80:83], v[108:111]
	s_waitcnt lgkmcnt(0)
	v_mfma_f32_16x16x32_bf16 v[116:119], v[112:115], v[72:75], 0
	v_mfma_f32_16x16x32_bf16 v[162:165], v[120:123], v[68:71], v[116:119]
	v_mfma_f32_16x16x32_bf16 v[112:115], v[112:115], v[76:79], 0
	s_nop 5
	ds_read_b128 v[116:119], v2 offset:4608
	v_max3_f32 v3, v3, v162, v163
	v_max3_f32 v3, v3, v164, v165
	v_mfma_f32_16x16x32_bf16 v[112:115], v[120:123], v[80:83], v[112:115]
	s_waitcnt lgkmcnt(0)
	v_mfma_f32_16x16x32_bf16 v[120:123], v[116:119], v[72:75], 0
	v_mfma_f32_16x16x32_bf16 v[176:179], v[166:169], v[68:71], v[120:123]
	s_nop 6
	ds_read_b128 v[120:123], v2 offset:6912
	v_mfma_f32_16x16x32_bf16 v[116:119], v[116:119], v[76:79], 0
	v_max3_f32 v3, v3, v176, v177
	v_max3_f32 v3, v3, v178, v179
	v_mfma_f32_16x16x32_bf16 v[116:119], v[166:169], v[80:83], v[116:119]
	s_waitcnt lgkmcnt(0)
	v_mfma_f32_16x16x32_bf16 v[166:169], v[120:123], v[72:75], 0
	v_mfma_f32_16x16x32_bf16 v[180:183], v[170:173], v[68:71], v[166:169]
	v_mfma_f32_16x16x32_bf16 v[120:123], v[120:123], v[76:79], 0
	v_mfma_f32_16x16x32_bf16 v[120:123], v[170:173], v[80:83], v[120:123]
	s_nop 5
	v_max3_f32 v3, v3, v180, v181
	v_max3_f32 v3, v3, v182, v183
	v_mov_b32_e32 v159, v3
	s_nop 1
	v_permlane16_swap_b32 v159, v3
	s_waitcnt lgkmcnt(0)
	v_max_f32_e32 v159, v159, v159
	v_max_f32_e32 v3, v3, v159
	v_mov_b32_e32 v159, v3
	s_nop 1
	v_permlane32_swap_b32 v159, v3
	s_waitcnt lgkmcnt(0)
	v_max3_f32 v159, v174, v3, v159
	v_sub_f32_e32 v3, v174, v159
	v_mul_f32_e32 v3, 0x3fb8aa3b, v3
	v_exp_f32_e32 v169, v3
	v_mul_f32_e32 v3, 0xbfb8aa3b, v159
	v_fmamk_f32 v124, v124, 0x3fb8aa3b, v3
	v_exp_f32_e32 v167, v124
	v_fmamk_f32 v125, v125, 0x3fb8aa3b, v3
	v_exp_f32_e32 v168, v125
	v_fmamk_f32 v125, v126, 0x3fb8aa3b, v3
	v_exp_f32_e32 v170, v125
	v_fmamk_f32 v125, v127, 0x3fb8aa3b, v3
	v_exp_f32_e32 v171, v125
	v_fmamk_f32 v125, v162, 0x3fb8aa3b, v3
	v_add_f32_e32 v124, 0, v167
	v_exp_f32_e32 v172, v125
	v_fmamk_f32 v125, v163, 0x3fb8aa3b, v3
	v_add_f32_e32 v124, v168, v124
	v_exp_f32_e32 v173, v125
	v_fmamk_f32 v125, v164, 0x3fb8aa3b, v3
	v_add_f32_e32 v124, v170, v124
	v_exp_f32_e32 v174, v125
	v_fmamk_f32 v125, v165, 0x3fb8aa3b, v3
	v_add_f32_e32 v124, v171, v124
	v_exp_f32_e32 v175, v125
	v_fmamk_f32 v125, v176, 0x3fb8aa3b, v3
	v_add_f32_e32 v124, v172, v124
	v_exp_f32_e32 v125, v125
	v_fmamk_f32 v126, v177, 0x3fb8aa3b, v3
	v_add_f32_e32 v124, v173, v124
	v_exp_f32_e32 v126, v126
	v_fmamk_f32 v127, v178, 0x3fb8aa3b, v3
	v_add_f32_e32 v124, v174, v124
	v_exp_f32_e32 v127, v127
	v_fmamk_f32 v162, v179, 0x3fb8aa3b, v3
	v_add_f32_e32 v124, v175, v124
	v_exp_f32_e32 v162, v162
	v_fmamk_f32 v163, v180, 0x3fb8aa3b, v3
	v_add_f32_e32 v124, v125, v124
	v_exp_f32_e32 v163, v163
	v_fmamk_f32 v164, v181, 0x3fb8aa3b, v3
	v_add_f32_e32 v124, v126, v124
	v_exp_f32_e32 v164, v164
	v_fmamk_f32 v165, v182, 0x3fb8aa3b, v3
	v_add_f32_e32 v124, v127, v124
	v_exp_f32_e32 v165, v165
	v_fmac_f32_e32 v3, 0x3fb8aa3b, v183
	v_add_f32_e32 v124, v162, v124
	v_exp_f32_e32 v166, v3
	v_add_f32_e32 v124, v163, v124
	v_add_f32_e32 v124, v164, v124
	v_add_f32_e32 v124, v165, v124
	v_add_f32_e32 v3, v166, v124
	v_mov_b32_e32 v124, v3
	s_nop 1
	v_permlane16_swap_b32 v124, v3
	v_cmp_neq_f32_e32 vcc, 1.0, v169
	s_waitcnt lgkmcnt(0)
	v_add_f32_e32 v3, v3, v124
	v_mov_b32_e32 v176, v3
	s_nop 1
	v_permlane32_swap_b32 v176, v3
	s_cbranch_vccz .LBB0_1312
	ds_bpermute_b32 v178, v146, v169
	ds_bpermute_b32 v180, v144, v169
	ds_bpermute_b32 v181, v145, v169
	ds_bpermute_b32 v179, v147, v169
	s_waitcnt lgkmcnt(1)
	v_pk_mul_f32 v[66:67], v[66:67], v[180:181]
	s_waitcnt lgkmcnt(0)
	v_pk_mul_f32 v[64:65], v[64:65], v[178:179]
	v_pk_mul_f32 v[58:59], v[58:59], v[180:181]
	v_pk_mul_f32 v[56:57], v[56:57], v[178:179]
	v_pk_mul_f32 v[50:51], v[50:51], v[180:181]
	v_pk_mul_f32 v[48:49], v[48:49], v[178:179]
	v_pk_mul_f32 v[42:43], v[42:43], v[180:181]
	v_pk_mul_f32 v[40:41], v[40:41], v[178:179]
	v_pk_mul_f32 v[34:35], v[34:35], v[180:181]
	v_pk_mul_f32 v[32:33], v[32:33], v[178:179]
	v_pk_mul_f32 v[26:27], v[26:27], v[180:181]
	v_pk_mul_f32 v[24:25], v[24:25], v[178:179]
	v_pk_mul_f32 v[18:19], v[18:19], v[180:181]
	v_pk_mul_f32 v[16:17], v[16:17], v[178:179]
	v_pk_mul_f32 v[14:15], v[14:15], v[180:181]
	v_pk_mul_f32 v[12:13], v[12:13], v[178:179]
.LBB0_1312:
	v_max3_f32 v124, v108, s76, v109
	v_max3_f32 v124, v124, v110, v111
	v_max3_f32 v124, v124, v112, v113
	v_max3_f32 v124, v124, v114, v115
	v_max3_f32 v124, v124, v116, v117
	v_max3_f32 v124, v124, v118, v119
	v_max3_f32 v124, v124, v120, v121
	v_max3_f32 v124, v124, v122, v123
	v_mov_b32_e32 v177, v124
	s_nop 1
	v_permlane16_swap_b32 v177, v124
	s_waitcnt lgkmcnt(0)
	v_max_f32_e32 v177, v177, v177
	v_max_f32_e32 v124, v124, v177
	v_mov_b32_e32 v177, v124
	s_nop 1
	v_permlane32_swap_b32 v177, v124
	s_waitcnt lgkmcnt(0)
	v_max3_f32 v124, v161, v124, v177
	v_mul_f32_e32 v178, 0xbfb8aa3b, v124
	v_fmamk_f32 v108, v108, 0x3fb8aa3b, v178
	v_fmamk_f32 v109, v109, 0x3fb8aa3b, v178
	v_exp_f32_e32 v108, v108
	v_fmamk_f32 v110, v110, 0x3fb8aa3b, v178
	v_exp_f32_e32 v109, v109
	v_fmamk_f32 v111, v111, 0x3fb8aa3b, v178
	v_exp_f32_e32 v110, v110
	v_fmamk_f32 v112, v112, 0x3fb8aa3b, v178
	v_exp_f32_e32 v111, v111
	v_fmamk_f32 v113, v113, 0x3fb8aa3b, v178
	v_exp_f32_e32 v112, v112
	v_add_f32_e32 v177, 0, v108
	v_fmamk_f32 v114, v114, 0x3fb8aa3b, v178
	v_exp_f32_e32 v113, v113
	v_add_f32_e32 v177, v109, v177
	v_add_f32_e32 v177, v110, v177
	v_exp_f32_e32 v114, v114
	v_fmamk_f32 v115, v115, 0x3fb8aa3b, v178
	v_add_f32_e32 v179, v111, v177
	v_exp_f32_e32 v177, v115
	v_fmamk_f32 v116, v116, 0x3fb8aa3b, v178
	v_add_f32_e32 v115, v112, v179
	v_exp_f32_e32 v116, v116
	v_fmamk_f32 v117, v117, 0x3fb8aa3b, v178
	v_add_f32_e32 v115, v113, v115
	v_exp_f32_e32 v117, v117
	v_fmamk_f32 v118, v118, 0x3fb8aa3b, v178
	v_add_f32_e32 v115, v114, v115
	v_exp_f32_e32 v118, v118
	v_fmamk_f32 v119, v119, 0x3fb8aa3b, v178
	v_add_f32_e32 v115, v177, v115
	v_exp_f32_e32 v119, v119
	v_fmamk_f32 v120, v120, 0x3fb8aa3b, v178
	v_add_f32_e32 v115, v116, v115
	v_exp_f32_e32 v120, v120
	v_fmamk_f32 v121, v121, 0x3fb8aa3b, v178
	v_add_f32_e32 v115, v117, v115
	v_exp_f32_e32 v121, v121
	v_fmamk_f32 v122, v122, 0x3fb8aa3b, v178
	v_add_f32_e32 v115, v118, v115
	v_exp_f32_e32 v122, v122
	v_fmac_f32_e32 v178, 0x3fb8aa3b, v123
	v_add_f32_e32 v115, v119, v115
	v_exp_f32_e32 v123, v178
	v_add_f32_e32 v115, v120, v115
	v_add_f32_e32 v115, v121, v115
	v_add_f32_e32 v115, v122, v115
	v_add_f32_e32 v115, v123, v115
	v_mov_b32_e32 v178, v115
	s_nop 1
	v_permlane16_swap_b32 v178, v115
	v_sub_f32_e32 v161, v161, v124
	v_mul_f32_e32 v161, 0x3fb8aa3b, v161
	v_exp_f32_e32 v161, v161
	s_waitcnt lgkmcnt(0)
	v_add_f32_e32 v115, v115, v178
	v_mov_b32_e32 v178, v115
	s_nop 1
	v_permlane32_swap_b32 v178, v115
	v_cmp_neq_f32_e32 vcc, 1.0, v161
	s_cbranch_vccz .LBB0_1314
	ds_bpermute_b32 v180, v146, v161
	ds_bpermute_b32 v182, v144, v161
	ds_bpermute_b32 v183, v145, v161
	ds_bpermute_b32 v181, v147, v161
	s_waitcnt lgkmcnt(1)
	v_pk_mul_f32 v[62:63], v[62:63], v[182:183]
	s_waitcnt lgkmcnt(0)
	v_pk_mul_f32 v[60:61], v[60:61], v[180:181]
	v_pk_mul_f32 v[54:55], v[54:55], v[182:183]
	v_pk_mul_f32 v[52:53], v[52:53], v[180:181]
	v_pk_mul_f32 v[46:47], v[46:47], v[182:183]
	v_pk_mul_f32 v[44:45], v[44:45], v[180:181]
	v_pk_mul_f32 v[38:39], v[38:39], v[182:183]
	v_pk_mul_f32 v[36:37], v[36:37], v[180:181]
	v_pk_mul_f32 v[30:31], v[30:31], v[182:183]
	v_pk_mul_f32 v[28:29], v[28:29], v[180:181]
	v_pk_mul_f32 v[22:23], v[22:23], v[182:183]
	v_pk_mul_f32 v[20:21], v[20:21], v[180:181]
	v_pk_mul_f32 v[10:11], v[10:11], v[182:183]
	v_pk_mul_f32 v[8:9], v[8:9], v[180:181]
	v_pk_mul_f32 v[6:7], v[6:7], v[182:183]
	v_pk_mul_f32 v[4:5], v[4:5], v[180:181]

.LBB0_1316:
	s_barrier
	s_waitcnt vmcnt(5)
	ds_write_b128 v154, v[84:87]
	s_waitcnt vmcnt(4)
	ds_write_b128 v155, v[88:91]
	s_waitcnt vmcnt(3)
	ds_write_b128 v154, v[92:95] offset:9216
	s_waitcnt vmcnt(2)
	ds_write_b128 v155, v[96:99] offset:9216
	s_waitcnt vmcnt(1)
	ds_write_b128 v156, v[100:103] offset:9216
	s_waitcnt vmcnt(0)
	ds_write_b128 v157, v[104:107] offset:9216
	s_waitcnt lgkmcnt(0)
	s_barrier
	ds_read_b128 v[84:87], v2
	ds_read_b128 v[92:95], v2 offset:64
	s_waitcnt lgkmcnt(1)
	v_mfma_f32_16x16x32_bf16 v[88:91], v[84:87], v[72:75], 0
	ds_read_b128 v[100:103], v2 offset:2368
	ds_read_b128 v[116:119], v2 offset:4672
	v_mfma_f32_16x16x32_bf16 v[84:87], v[84:87], v[76:79], 0
	s_waitcnt lgkmcnt(2)
	v_mfma_f32_16x16x32_bf16 v[96:99], v[92:95], v[68:71], v[88:91]
	v_mfma_f32_16x16x32_bf16 v[92:95], v[92:95], v[80:83], v[84:87]
	s_nop 4
	ds_read_b128 v[84:87], v2 offset:2304
	s_waitcnt lgkmcnt(0)
	v_mfma_f32_16x16x32_bf16 v[88:91], v[84:87], v[72:75], 0
	v_mfma_f32_16x16x32_bf16 v[84:87], v[84:87], v[76:79], 0
	v_mfma_f32_16x16x32_bf16 v[104:107], v[100:103], v[68:71], v[88:91]
	v_mfma_f32_16x16x32_bf16 v[88:91], v[100:103], v[80:83], v[84:87]
	s_nop 5
	ds_read_b128 v[84:87], v2 offset:4608
	s_waitcnt lgkmcnt(0)
	v_mfma_f32_16x16x32_bf16 v[100:103], v[84:87], v[72:75], 0
	v_mfma_f32_16x16x32_bf16 v[84:87], v[84:87], v[76:79], 0
	v_mfma_f32_16x16x32_bf16 v[100:103], v[116:119], v[68:71], v[100:103]
	v_mfma_f32_16x16x32_bf16 v[84:87], v[116:119], v[80:83], v[84:87]
	ds_read_b128 v[116:119], v2 offset:6912
	s_waitcnt lgkmcnt(0)
	v_mfma_f32_16x16x32_bf16 v[72:75], v[116:119], v[72:75], 0
	v_mfma_f32_16x16x32_bf16 v[76:79], v[116:119], v[76:79], 0
	ds_read_b128 v[116:119], v2 offset:6976
	v_max3_f32 v2, v96, s76, v97
	v_max3_f32 v2, v2, v98, v99
	s_waitcnt lgkmcnt(0)
	v_mfma_f32_16x16x32_bf16 v[120:123], v[116:119], v[68:71], v[72:75]
	v_max3_f32 v2, v2, v104, v105
	v_max3_f32 v2, v2, v106, v107
	v_max3_f32 v2, v2, v100, v101
	v_max3_f32 v2, v2, v102, v103
	s_nop 3
	v_max3_f32 v2, v2, v120, v121
	v_max3_f32 v2, v2, v122, v123
	v_mov_b32_e32 v72, v2
	s_nop 1
	v_permlane16_swap_b32 v72, v2
	v_mfma_f32_16x16x32_bf16 v[68:71], v[116:119], v[80:83], v[76:79]
	s_waitcnt lgkmcnt(0)
	v_max_f32_e32 v72, v72, v72
	v_max_f32_e32 v2, v2, v72
	v_mov_b32_e32 v72, v2
	s_nop 1
	v_permlane32_swap_b32 v72, v2
	s_waitcnt lgkmcnt(0)
	v_max3_f32 v2, v159, v2, v72
	v_sub_f32_e32 v72, v159, v2
	v_mul_f32_e32 v78, 0xbfb8aa3b, v2
	v_mul_f32_e32 v72, 0x3fb8aa3b, v72
	v_fmamk_f32 v2, v96, 0x3fb8aa3b, v78
	v_exp_f32_e32 v80, v72
	v_exp_f32_e32 v79, v2
	v_fmamk_f32 v72, v97, 0x3fb8aa3b, v78
	v_exp_f32_e32 v81, v72
	v_fmamk_f32 v72, v98, 0x3fb8aa3b, v78
	v_exp_f32_e32 v82, v72
	v_fmamk_f32 v72, v99, 0x3fb8aa3b, v78
	v_exp_f32_e32 v83, v72
	v_fmamk_f32 v72, v104, 0x3fb8aa3b, v78
	v_add_f32_e32 v2, 0, v79
	v_exp_f32_e32 v96, v72
	v_fmamk_f32 v72, v105, 0x3fb8aa3b, v78
	v_add_f32_e32 v2, v81, v2
	v_exp_f32_e32 v97, v72
	v_fmamk_f32 v72, v106, 0x3fb8aa3b, v78
	v_add_f32_e32 v2, v82, v2
	v_exp_f32_e32 v98, v72
	v_fmamk_f32 v72, v107, 0x3fb8aa3b, v78
	v_add_f32_e32 v2, v83, v2
	v_exp_f32_e32 v99, v72
	v_add_f32_e32 v2, v96, v2
	v_add_f32_e32 v2, v97, v2
	v_add_f32_e32 v2, v98, v2
	v_add_f32_e32 v72, v99, v2
	v_fmamk_f32 v2, v100, 0x3fb8aa3b, v78
	v_exp_f32_e32 v2, v2
	v_cmp_neq_f32_e32 vcc, 1.0, v80
	v_add_f32_e32 v73, v2, v72
	v_fmamk_f32 v72, v101, 0x3fb8aa3b, v78
	v_exp_f32_e32 v72, v72
	s_nop 0
	v_add_f32_e32 v74, v72, v73
	v_fmamk_f32 v73, v102, 0x3fb8aa3b, v78
	v_exp_f32_e32 v73, v73
	s_nop 0
	v_add_f32_e32 v75, v73, v74
	v_fmamk_f32 v74, v103, 0x3fb8aa3b, v78
	v_exp_f32_e32 v74, v74
	s_nop 0
	v_add_f32_e32 v76, v74, v75
	v_fmamk_f32 v75, v120, 0x3fb8aa3b, v78
	v_exp_f32_e32 v75, v75
	s_nop 0
	v_add_f32_e32 v77, v75, v76
	v_fmamk_f32 v76, v121, 0x3fb8aa3b, v78
	v_exp_f32_e32 v76, v76
	s_nop 0
	v_add_f32_e32 v100, v76, v77
	v_fmamk_f32 v77, v122, 0x3fb8aa3b, v78
	v_exp_f32_e32 v77, v77
	v_fmac_f32_e32 v78, 0x3fb8aa3b, v123
	v_exp_f32_e32 v78, v78
	v_add_f32_e32 v100, v77, v100
	v_add_f32_e32 v100, v78, v100
	v_mov_b32_e32 v101, v100
	s_nop 1
	v_permlane16_swap_b32 v101, v100
	s_waitcnt lgkmcnt(0)
	v_add_f32_e32 v100, v100, v101
	v_mov_b32_e32 v101, v100
	s_nop 1
	v_permlane32_swap_b32 v101, v100
	s_cbranch_vccz .LBB0_1318
	ds_bpermute_b32 v102, v146, v80
	ds_bpermute_b32 v104, v144, v80
	ds_bpermute_b32 v105, v145, v80
	ds_bpermute_b32 v103, v147, v80
	s_waitcnt lgkmcnt(1)
	v_pk_mul_f32 v[66:67], v[66:67], v[104:105]
	s_waitcnt lgkmcnt(0)
	v_pk_mul_f32 v[64:65], v[64:65], v[102:103]
	v_pk_mul_f32 v[58:59], v[58:59], v[104:105]
	v_pk_mul_f32 v[56:57], v[56:57], v[102:103]
	v_pk_mul_f32 v[50:51], v[50:51], v[104:105]
	v_pk_mul_f32 v[48:49], v[48:49], v[102:103]
	v_pk_mul_f32 v[42:43], v[42:43], v[104:105]
	v_pk_mul_f32 v[40:41], v[40:41], v[102:103]
	v_pk_mul_f32 v[34:35], v[34:35], v[104:105]
	v_pk_mul_f32 v[32:33], v[32:33], v[102:103]
	v_pk_mul_f32 v[26:27], v[26:27], v[104:105]
	v_pk_mul_f32 v[24:25], v[24:25], v[102:103]
	v_pk_mul_f32 v[18:19], v[18:19], v[104:105]
	v_pk_mul_f32 v[16:17], v[16:17], v[102:103]
	v_pk_mul_f32 v[14:15], v[14:15], v[104:105]
	v_pk_mul_f32 v[12:13], v[12:13], v[102:103]
.LBB0_1318:
	v_max3_f32 v102, v92, s76, v93
	v_max3_f32 v102, v102, v94, v95
	v_max3_f32 v102, v102, v88, v89
	v_max3_f32 v102, v102, v90, v91
	v_max3_f32 v102, v102, v84, v85
	v_max3_f32 v102, v102, v86, v87
	v_max3_f32 v102, v102, v68, v69
	v_max3_f32 v102, v102, v70, v71
	v_mov_b32_e32 v103, v102
	s_nop 1
	v_permlane16_swap_b32 v103, v102
	s_waitcnt lgkmcnt(0)
	v_max_f32_e32 v103, v103, v103
	v_max_f32_e32 v102, v102, v103
	v_mov_b32_e32 v103, v102
	s_nop 1
	v_permlane32_swap_b32 v103, v102
	s_waitcnt lgkmcnt(0)
	v_max3_f32 v103, v124, v102, v103
	v_mul_f32_e32 v104, 0xbfb8aa3b, v103
	v_fmamk_f32 v92, v92, 0x3fb8aa3b, v104
	v_exp_f32_e32 v92, v92
	v_fmamk_f32 v93, v93, 0x3fb8aa3b, v104
	v_exp_f32_e32 v93, v93
	v_fmamk_f32 v94, v94, 0x3fb8aa3b, v104
	v_exp_f32_e32 v94, v94
	v_fmamk_f32 v95, v95, 0x3fb8aa3b, v104
	v_exp_f32_e32 v95, v95
	v_sub_f32_e32 v102, v124, v103
	v_add_f32_e32 v103, 0, v92
	v_add_f32_e32 v103, v93, v103
	v_add_f32_e32 v103, v94, v103
	v_fmamk_f32 v88, v88, 0x3fb8aa3b, v104
	v_add_f32_e32 v105, v95, v103
	v_exp_f32_e32 v103, v88
	v_fmamk_f32 v89, v89, 0x3fb8aa3b, v104
	v_exp_f32_e32 v89, v89
	v_fmamk_f32 v90, v90, 0x3fb8aa3b, v104
	v_exp_f32_e32 v90, v90
	v_fmamk_f32 v91, v91, 0x3fb8aa3b, v104
	v_exp_f32_e32 v91, v91
	v_add_f32_e32 v88, v103, v105
	v_add_f32_e32 v88, v89, v88
	v_add_f32_e32 v88, v90, v88
	v_fmamk_f32 v84, v84, 0x3fb8aa3b, v104
	v_add_f32_e32 v105, v91, v88
	v_exp_f32_e32 v88, v84
	v_fmamk_f32 v85, v85, 0x3fb8aa3b, v104
	v_exp_f32_e32 v85, v85
	v_fmamk_f32 v86, v86, 0x3fb8aa3b, v104
	v_exp_f32_e32 v86, v86
	v_fmamk_f32 v87, v87, 0x3fb8aa3b, v104
	v_exp_f32_e32 v87, v87
	v_fmamk_f32 v68, v68, 0x3fb8aa3b, v104
	v_add_f32_e32 v84, v88, v105
	v_exp_f32_e32 v68, v68
	v_fmamk_f32 v69, v69, 0x3fb8aa3b, v104
	v_add_f32_e32 v84, v85, v84
	v_exp_f32_e32 v69, v69
	v_fmamk_f32 v70, v70, 0x3fb8aa3b, v104
	v_add_f32_e32 v84, v86, v84
	v_exp_f32_e32 v70, v70
	v_fmac_f32_e32 v104, 0x3fb8aa3b, v71
	v_add_f32_e32 v84, v87, v84
	v_exp_f32_e32 v71, v104
	v_add_f32_e32 v84, v68, v84
	v_add_f32_e32 v84, v69, v84
	v_add_f32_e32 v84, v70, v84
	v_add_f32_e32 v84, v71, v84
	v_mov_b32_e32 v104, v84
	s_nop 1
	v_permlane16_swap_b32 v104, v84
	v_mul_f32_e32 v102, 0x3fb8aa3b, v102
	v_exp_f32_e32 v102, v102
	s_waitcnt lgkmcnt(0)
	v_add_f32_e32 v84, v84, v104
	v_mov_b32_e32 v104, v84
	s_nop 1
	v_permlane32_swap_b32 v104, v84
	v_cmp_neq_f32_e32 vcc, 1.0, v102
	s_cbranch_vccz .LBB0_1320
	ds_bpermute_b32 v106, v146, v102
	ds_bpermute_b32 v116, v144, v102
	ds_bpermute_b32 v117, v145, v102
	ds_bpermute_b32 v107, v147, v102
	s_waitcnt lgkmcnt(1)
	v_pk_mul_f32 v[62:63], v[62:63], v[116:117]
	s_waitcnt lgkmcnt(0)
	v_pk_mul_f32 v[60:61], v[60:61], v[106:107]
	v_pk_mul_f32 v[54:55], v[54:55], v[116:117]
	v_pk_mul_f32 v[52:53], v[52:53], v[106:107]
	v_pk_mul_f32 v[46:47], v[46:47], v[116:117]
	v_pk_mul_f32 v[44:45], v[44:45], v[106:107]
	v_pk_mul_f32 v[38:39], v[38:39], v[116:117]
	v_pk_mul_f32 v[36:37], v[36:37], v[106:107]
	v_pk_mul_f32 v[30:31], v[30:31], v[116:117]
	v_pk_mul_f32 v[28:29], v[28:29], v[106:107]
	v_pk_mul_f32 v[22:23], v[22:23], v[116:117]
	v_pk_mul_f32 v[20:21], v[20:21], v[106:107]
	v_pk_mul_f32 v[10:11], v[10:11], v[116:117]
	v_pk_mul_f32 v[8:9], v[8:9], v[106:107]
	v_pk_mul_f32 v[6:7], v[6:7], v[116:117]
	v_pk_mul_f32 v[4:5], v[4:5], v[106:107]
